# in-proj GEMM: peeled first K-iteration of non-first tiles waits with vmcnt(16/24) according to the previous tile's store count (strict for the mixed kv tiles)
# baseline (speedup 1.0000x reference)
.LBB0_155:
	s_lshl_b32 s1, s1, 5
	s_and_b32 s1, s1, 0x60
	s_ashr_i32 s81, s38, 31
	s_ashr_i32 s54, s33, 31
	s_lshl_b32 s5, s0, 13
	s_lshl_b32 s8, s1, 7
	s_add_u32 s62, s68, 0x9ba0000
	s_addc_u32 s63, s69, 0
	s_add_u32 s60, s68, 0xa7a0000
	s_mov_b64 s[82:83], 0x80
	s_addc_u32 s61, s69, 0
	s_add_i32 m0, s7, 0x18000
	v_lshl_add_u64 v[6:7], v[6:7], 0, s[82:83]
	s_waitcnt vmcnt(2)
	s_barrier
	global_load_lds_dwordx4 v[6:7], off
	v_lshl_add_u64 v[4:5], v[4:5], 0, s[82:83]
	s_add_i32 m0, s7, 0x1a000
	s_add_i32 s55, s7, 0x8000
	s_add_i32 s56, s7, 0xa000
	global_load_lds_dwordx4 v[4:5], off
	v_lshl_add_u64 v[2:3], v[2:3], 0, s[82:83]
	s_mov_b32 m0, s55
	s_add_u32 s12, s96, 0x40080
	global_load_lds_dwordx4 v[2:3], off
	v_lshl_add_u64 v[0:1], v[0:1], 0, s[82:83]
	s_mov_b32 m0, s56
	s_addc_u32 s13, s97, 0
	global_load_lds_dwordx4 v[0:1], off
	s_add_i32 m0, s7, 0x1c000
	v_lshl_add_u64 v[0:1], s[12:13], 0, v[130:131]
	global_load_lds_dwordx4 v[0:1], off
	v_lshl_add_u64 v[0:1], s[12:13], 0, v[134:135]
	s_add_i32 m0, s7, 0x1e000
	s_cmpk_lt_u32 s3, 0x100
	global_load_lds_dwordx4 v[0:1], off
	v_lshrrev_b32_e32 v1, 1, v8
	v_and_b32_e32 v1, 24, v1
	v_and_b32_e32 v0, 15, v8
	v_lshlrev_b32_e32 v2, 1, v1
	v_lshl_or_b32 v139, s0, 6, v0
	v_lshl_or_b32 v0, v0, 6, v2
	v_lshlrev_b32_e32 v2, 2, v8
	v_and_b32_e32 v2, 32, v2
	v_bitop3_b32 v3, v0, s5, v2 bitop3:0xde
	v_bitop3_b32 v150, v0, s8, v2 bitop3:0xde
	v_lshlrev_b32_e32 v0, 14, v9
	v_and_b32_e32 v0, 0xffff8000, v0
	v_or_b32_e32 v138, s1, v1
	v_lshl_add_u32 v0, v10, 11, v0
	v_and_b32_e32 v1, 1, v9
	v_lshl_or_b32 v0, v1, 6, v0
	v_lshl_add_u32 v140, v11, 1, v0
	v_lshlrev_b32_e32 v0, 14, v12
	v_and_b32_e32 v0, 0xffff8000, v0
	s_waitcnt vmcnt(6)
	v_lshl_add_u32 v0, v13, 11, v0
	v_and_b32_e32 v1, 1, v12
	s_cselect_b64 s[84:85], -1, 0
	v_lshl_or_b32 v0, v1, 6, v0
	s_add_i32 s58, 0, 0x10000
	s_add_i32 s59, 0, 0x14000
	s_mov_b32 s57, s38
	v_or_b32_e32 v151, 16, v139
	v_or_b32_e32 v152, 32, v139
	v_or_b32_e32 v153, 48, v139
	v_add_u32_e32 v154, 0x80, v139
	v_add_u32_e32 v155, 0x90, v139
	v_add_u32_e32 v156, 0xa0, v139
	v_add_u32_e32 v157, 0xb0, v139
	v_mov_b32_e32 v141, v137
	v_lshl_add_u32 v142, v14, 1, v0
	v_mov_b32_e32 v143, v137
	v_mov_b64_e32 v[144:145], 0x5ee
	v_mov_b64_e32 v[146:147], 0x5ed
	v_add_u32_e32 v158, s58, v150
	v_add_u32_e32 v159, s59, v150
	v_add_u32_e32 v160, 0, v3
	s_movk_i32 s71, 0x17f
	s_mov_b32 s64, 0
	s_barrier
	s_mov_b32 s32, 0
	s_branch .LBB0_158

.Lp2_keep:
	s_ashr_i32 s89, s88, 31
	s_lshl_b64 s[12:13], s[88:89], 19
	s_add_u32 s90, s34, s12
	s_addc_u32 s91, s35, s13
	s_and_b64 s[12:13], s[0:1], exec
	s_cselect_b32 s3, s91, s95
	s_cselect_b32 s5, s90, s94
	s_ashr_i32 s87, s86, 31
	s_lshl_b64 s[12:13], s[86:87], 19
	s_add_u32 s92, s14, s12
	s_addc_u32 s93, s15, s13
	s_and_b64 s[12:13], s[0:1], exec
	s_cselect_b32 s8, s93, s97
	s_cselect_b32 s12, s92, s96
	s_add_u32 s94, s94, 0x40080
	s_addc_u32 s95, s95, 0
	s_add_u32 s13, s96, 0x100
	s_addc_u32 s52, s97, 0
	s_mov_b32 s53, -2
	ds_read_b128 v[162:165], v158
	ds_read_b128 v[166:169], v158 offset:1024
	ds_read_b128 v[170:173], v158 offset:2048
	ds_read_b128 v[174:177], v158 offset:3072
	ds_read_b128 v[178:181], v159
	ds_read_b128 v[182:185], v159 offset:1024
	ds_read_b128 v[186:189], v159 offset:2048
	ds_read_b128 v[190:193], v159 offset:3072
	s_add_u32 s65, s94, 0xfffc0080
	s_addc_u32 s66, s95, -1
	s_cmp_eq_u32 s53, 12
	s_cselect_b32 vcc_hi, s3, s66
	s_cselect_b32 vcc_lo, s5, s65
	s_cselect_b32 s97, s8, s52
	s_cselect_b32 s96, s12, s13
	v_lshl_add_u64 v[148:149], s[94:95], 0, v[140:141]
	s_add_i32 m0, s7, 0xc000
	ds_read_b128 v[198:201], v160
	ds_read_b128 v[202:205], v160 offset:1024
	ds_read_b128 v[206:209], v160 offset:2048
	ds_read_b128 v[210:213], v160 offset:3072
	ds_read_b128 v[214:217], v160 offset:4096
	ds_read_b128 v[218:221], v160 offset:5120
	ds_read_b128 v[222:225], v160 offset:6144
	ds_read_b128 v[226:229], v160 offset:7168
	global_load_lds_dwordx4 v[148:149], off
	v_lshl_add_u64 v[148:149], s[94:95], 0, v[142:143]
	s_add_i32 m0, s7, 0xe000
	s_nop 0
	global_load_lds_dwordx4 v[148:149], off
	s_cmp_eq_u32 s32, 0
	s_cbranch_scc1 .Lp2_ws0
	s_cmp_eq_u32 s32, 1
	s_cbranch_scc1 .Lp2_wm0
	s_waitcnt vmcnt(24)
	s_branch .Lp2_wd0
.Lp2_wm0:
	s_waitcnt vmcnt(16)
	s_branch .Lp2_wd0

.Lp2_wd0:
	s_waitcnt lgkmcnt(0)
	s_barrier
	s_setprio 1
	s_waitcnt lgkmcnt(0)
	v_mfma_f32_16x16x32_bf16 v[124:127], v[162:165], v[198:201], 0
	v_mfma_f32_16x16x32_bf16 v[120:123], v[170:173], v[198:201], 0
	v_mfma_f32_16x16x32_bf16 v[108:111], v[162:165], v[206:209], 0
	v_mfma_f32_16x16x32_bf16 v[104:107], v[170:173], v[206:209], 0
	v_mfma_f32_16x16x32_bf16 v[92:95], v[162:165], v[214:217], 0
	v_mfma_f32_16x16x32_bf16 v[88:91], v[170:173], v[214:217], 0
	v_mfma_f32_16x16x32_bf16 v[76:79], v[162:165], v[222:225], 0
	v_mfma_f32_16x16x32_bf16 v[72:75], v[170:173], v[222:225], 0
	v_mfma_f32_16x16x32_bf16 v[124:127], v[166:169], v[202:205], v[124:127]
	v_mfma_f32_16x16x32_bf16 v[120:123], v[174:177], v[202:205], v[120:123]
	v_mfma_f32_16x16x32_bf16 v[108:111], v[166:169], v[210:213], v[108:111]
	v_mfma_f32_16x16x32_bf16 v[104:107], v[174:177], v[210:213], v[104:107]
	v_mfma_f32_16x16x32_bf16 v[92:95], v[166:169], v[218:221], v[92:95]
	v_mfma_f32_16x16x32_bf16 v[88:91], v[174:177], v[218:221], v[88:91]
	v_mfma_f32_16x16x32_bf16 v[76:79], v[166:169], v[226:229], v[76:79]
	v_mfma_f32_16x16x32_bf16 v[72:75], v[174:177], v[226:229], v[72:75]
	s_setprio 0
	s_setprio 1
	v_mfma_f32_16x16x32_bf16 v[116:119], v[178:181], v[198:201], 0
	v_mfma_f32_16x16x32_bf16 v[112:115], v[186:189], v[198:201], 0
	v_mfma_f32_16x16x32_bf16 v[100:103], v[178:181], v[206:209], 0
	v_mfma_f32_16x16x32_bf16 v[96:99], v[186:189], v[206:209], 0
	v_mfma_f32_16x16x32_bf16 v[84:87], v[178:181], v[214:217], 0
	v_mfma_f32_16x16x32_bf16 v[80:83], v[186:189], v[214:217], 0
	v_mfma_f32_16x16x32_bf16 v[68:71], v[178:181], v[222:225], 0
	v_mfma_f32_16x16x32_bf16 v[64:67], v[186:189], v[222:225], 0
	v_mfma_f32_16x16x32_bf16 v[116:119], v[182:185], v[202:205], v[116:119]
	v_mfma_f32_16x16x32_bf16 v[112:115], v[190:193], v[202:205], v[112:115]
	v_mfma_f32_16x16x32_bf16 v[100:103], v[182:185], v[210:213], v[100:103]
	v_mfma_f32_16x16x32_bf16 v[96:99], v[190:193], v[210:213], v[96:99]
	v_mfma_f32_16x16x32_bf16 v[84:87], v[182:185], v[218:221], v[84:87]
	v_mfma_f32_16x16x32_bf16 v[80:83], v[190:193], v[218:221], v[80:83]
	v_mfma_f32_16x16x32_bf16 v[68:71], v[182:185], v[226:229], v[68:71]
	v_mfma_f32_16x16x32_bf16 v[64:67], v[190:193], v[226:229], v[64:67]
	s_setprio 0
	s_barrier
	s_add_i32 s65, s58, s75
	v_lshl_add_u64 v[148:149], s[96:97], 0, v[130:131]
	s_mov_b32 m0, s65
	ds_read_b128 v[198:201], v160 offset:16384
	ds_read_b128 v[202:205], v160 offset:17408
	ds_read_b128 v[206:209], v160 offset:18432
	ds_read_b128 v[210:213], v160 offset:19456
	ds_read_b128 v[214:217], v160 offset:20480
	ds_read_b128 v[218:221], v160 offset:21504
	ds_read_b128 v[222:225], v160 offset:22528
	ds_read_b128 v[226:229], v160 offset:23552
	global_load_lds_dwordx4 v[148:149], off
	s_add_i32 m0, s65, 0x2000
	s_add_u32 s66, s96, 0x40000
	v_lshl_add_u64 v[194:195], s[96:97], 0, v[134:135]
	s_addc_u32 s67, s97, 0
	s_add_i32 s65, s59, s75
	global_load_lds_dwordx4 v[194:195], off
	v_lshl_add_u64 v[230:231], s[66:67], 0, v[130:131]
	s_mov_b32 m0, s65
	v_lshl_add_u64 v[232:233], vcc, 0, v[132:133]
	global_load_lds_dwordx4 v[230:231], off
	v_lshl_add_u64 v[230:231], s[66:67], 0, v[134:135]
	s_add_i32 m0, s65, 0x2000
	s_nop 0
	global_load_lds_dwordx4 v[230:231], off
	v_lshl_add_u64 v[230:231], vcc, 0, v[128:129]
	s_mov_b32 m0, s7
	s_nop 0
	global_load_lds_dwordx4 v[230:231], off
	s_mov_b32 m0, s77
	s_nop 0
	global_load_lds_dwordx4 v[232:233], off
	s_cmp_eq_u32 s32, 0
	s_cbranch_scc1 .Lp2_ws1
	s_cmp_eq_u32 s32, 1
	s_cbranch_scc1 .Lp2_wm1
	s_waitcnt vmcnt(24)
	s_branch .Lp2_wd1

.Lp2_wd1:
	s_waitcnt lgkmcnt(0)
	s_barrier
	s_setprio 1
	s_waitcnt lgkmcnt(0)
	v_mfma_f32_16x16x32_bf16 v[60:63], v[162:165], v[198:201], 0
	v_mfma_f32_16x16x32_bf16 v[56:59], v[170:173], v[198:201], 0
	v_mfma_f32_16x16x32_bf16 v[44:47], v[162:165], v[206:209], 0
	v_mfma_f32_16x16x32_bf16 v[40:43], v[170:173], v[206:209], 0
	v_mfma_f32_16x16x32_bf16 v[28:31], v[162:165], v[214:217], 0
	v_mfma_f32_16x16x32_bf16 v[24:27], v[170:173], v[214:217], 0
	v_mfma_f32_16x16x32_bf16 v[12:15], v[162:165], v[222:225], 0
	v_mfma_f32_16x16x32_bf16 v[8:11], v[170:173], v[222:225], 0
	v_mfma_f32_16x16x32_bf16 v[60:63], v[166:169], v[202:205], v[60:63]
	v_mfma_f32_16x16x32_bf16 v[56:59], v[174:177], v[202:205], v[56:59]
	v_mfma_f32_16x16x32_bf16 v[44:47], v[166:169], v[210:213], v[44:47]
	v_mfma_f32_16x16x32_bf16 v[40:43], v[174:177], v[210:213], v[40:43]
	v_mfma_f32_16x16x32_bf16 v[28:31], v[166:169], v[218:221], v[28:31]
	v_mfma_f32_16x16x32_bf16 v[24:27], v[174:177], v[218:221], v[24:27]
	v_mfma_f32_16x16x32_bf16 v[12:15], v[166:169], v[226:229], v[12:15]
	v_mfma_f32_16x16x32_bf16 v[8:11], v[174:177], v[226:229], v[8:11]
	s_setprio 0
	s_setprio 1
	v_mfma_f32_16x16x32_bf16 v[52:55], v[178:181], v[198:201], 0
	v_mfma_f32_16x16x32_bf16 v[48:51], v[186:189], v[198:201], 0
	v_mfma_f32_16x16x32_bf16 v[36:39], v[178:181], v[206:209], 0
	v_mfma_f32_16x16x32_bf16 v[32:35], v[186:189], v[206:209], 0
	v_mfma_f32_16x16x32_bf16 v[20:23], v[178:181], v[214:217], 0
	v_mfma_f32_16x16x32_bf16 v[16:19], v[186:189], v[214:217], 0
	v_mfma_f32_16x16x32_bf16 v[4:7], v[178:181], v[222:225], 0
	v_mfma_f32_16x16x32_bf16 v[0:3], v[186:189], v[222:225], 0
	v_mfma_f32_16x16x32_bf16 v[52:55], v[182:185], v[202:205], v[52:55]
	v_mfma_f32_16x16x32_bf16 v[48:51], v[190:193], v[202:205], v[48:51]
	v_mfma_f32_16x16x32_bf16 v[36:39], v[182:185], v[210:213], v[36:39]
	v_mfma_f32_16x16x32_bf16 v[32:35], v[190:193], v[210:213], v[32:35]
	v_mfma_f32_16x16x32_bf16 v[20:23], v[182:185], v[218:221], v[20:23]
	v_mfma_f32_16x16x32_bf16 v[16:19], v[190:193], v[218:221], v[16:19]
	v_mfma_f32_16x16x32_bf16 v[4:7], v[182:185], v[226:229], v[4:7]
	v_mfma_f32_16x16x32_bf16 v[0:3], v[190:193], v[226:229], v[0:3]
	s_setprio 0
	s_barrier
	s_add_i32 s65, 0, 0x18000
	v_add_u32_e32 v136, s65, v150
	s_add_i32 s70, 0, 0x1c000
	ds_read_b128 v[162:165], v136
	ds_read_b128 v[166:169], v136 offset:1024
	ds_read_b128 v[170:173], v136 offset:2048
	ds_read_b128 v[174:177], v136 offset:3072
	v_add_u32_e32 v136, s70, v150
	ds_read_b128 v[178:181], v136
	ds_read_b128 v[182:185], v136 offset:1024
	ds_read_b128 v[186:189], v136 offset:2048
	ds_read_b128 v[190:193], v136 offset:3072
	s_add_u32 s66, vcc_lo, 0x40000
	s_addc_u32 s67, vcc_hi, 0
	s_mov_b32 m0, s78
	v_lshl_add_u64 v[234:235], s[66:67], 0, v[128:129]
	ds_read_b128 v[198:201], v160 offset:32768
	ds_read_b128 v[202:205], v160 offset:33792
	ds_read_b128 v[206:209], v160 offset:34816
	ds_read_b128 v[210:213], v160 offset:35840
	ds_read_b128 v[214:217], v160 offset:36864
	ds_read_b128 v[218:221], v160 offset:37888
	ds_read_b128 v[222:225], v160 offset:38912
	ds_read_b128 v[226:229], v160 offset:39936
	global_load_lds_dwordx4 v[234:235], off
	v_lshl_add_u64 v[234:235], s[66:67], 0, v[132:133]
	s_mov_b32 m0, s79
	s_nop 0
	global_load_lds_dwordx4 v[234:235], off
	s_waitcnt vmcnt(8)
	s_waitcnt lgkmcnt(0)
	s_barrier
	s_setprio 1
	s_waitcnt lgkmcnt(0)
	v_mfma_f32_16x16x32_bf16 v[124:127], v[162:165], v[198:201], v[124:127]
	v_mfma_f32_16x16x32_bf16 v[120:123], v[170:173], v[198:201], v[120:123]
	v_mfma_f32_16x16x32_bf16 v[108:111], v[162:165], v[206:209], v[108:111]
	v_mfma_f32_16x16x32_bf16 v[104:107], v[170:173], v[206:209], v[104:107]
	v_mfma_f32_16x16x32_bf16 v[92:95], v[162:165], v[214:217], v[92:95]
	v_mfma_f32_16x16x32_bf16 v[88:91], v[170:173], v[214:217], v[88:91]
	v_mfma_f32_16x16x32_bf16 v[76:79], v[162:165], v[222:225], v[76:79]
	v_mfma_f32_16x16x32_bf16 v[72:75], v[170:173], v[222:225], v[72:75]
	v_mfma_f32_16x16x32_bf16 v[124:127], v[166:169], v[202:205], v[124:127]
	v_mfma_f32_16x16x32_bf16 v[120:123], v[174:177], v[202:205], v[120:123]
	v_mfma_f32_16x16x32_bf16 v[108:111], v[166:169], v[210:213], v[108:111]
	v_mfma_f32_16x16x32_bf16 v[104:107], v[174:177], v[210:213], v[104:107]
	v_mfma_f32_16x16x32_bf16 v[92:95], v[166:169], v[218:221], v[92:95]
	v_mfma_f32_16x16x32_bf16 v[88:91], v[174:177], v[218:221], v[88:91]
	v_mfma_f32_16x16x32_bf16 v[76:79], v[166:169], v[226:229], v[76:79]
	v_mfma_f32_16x16x32_bf16 v[72:75], v[174:177], v[226:229], v[72:75]
	s_setprio 0
	s_setprio 1
	v_mfma_f32_16x16x32_bf16 v[116:119], v[178:181], v[198:201], v[116:119]
	v_mfma_f32_16x16x32_bf16 v[112:115], v[186:189], v[198:201], v[112:115]
	v_mfma_f32_16x16x32_bf16 v[100:103], v[178:181], v[206:209], v[100:103]
	v_mfma_f32_16x16x32_bf16 v[96:99], v[186:189], v[206:209], v[96:99]
	v_mfma_f32_16x16x32_bf16 v[84:87], v[178:181], v[214:217], v[84:87]
	v_mfma_f32_16x16x32_bf16 v[80:83], v[186:189], v[214:217], v[80:83]
	v_mfma_f32_16x16x32_bf16 v[68:71], v[178:181], v[222:225], v[68:71]
	v_mfma_f32_16x16x32_bf16 v[64:67], v[186:189], v[222:225], v[64:67]
	v_mfma_f32_16x16x32_bf16 v[116:119], v[182:185], v[202:205], v[116:119]
	v_mfma_f32_16x16x32_bf16 v[112:115], v[190:193], v[202:205], v[112:115]
	v_mfma_f32_16x16x32_bf16 v[100:103], v[182:185], v[210:213], v[100:103]
	v_mfma_f32_16x16x32_bf16 v[96:99], v[190:193], v[210:213], v[96:99]
	v_mfma_f32_16x16x32_bf16 v[84:87], v[182:185], v[218:221], v[84:87]
	v_mfma_f32_16x16x32_bf16 v[80:83], v[190:193], v[218:221], v[80:83]
	v_mfma_f32_16x16x32_bf16 v[68:71], v[182:185], v[226:229], v[68:71]
	v_mfma_f32_16x16x32_bf16 v[64:67], v[190:193], v[226:229], v[64:67]
	s_setprio 0
	s_barrier
	s_add_i32 s65, s65, s75
	v_lshl_add_u64 v[148:149], v[148:149], 0, s[82:83]
	s_mov_b32 m0, s65
	ds_read_b128 v[198:201], v160 offset:49152
	ds_read_b128 v[202:205], v160 offset:50176
	ds_read_b128 v[206:209], v160 offset:51200
	ds_read_b128 v[210:213], v160 offset:52224
	ds_read_b128 v[214:217], v160 offset:53248
	ds_read_b128 v[218:221], v160 offset:54272
	ds_read_b128 v[222:225], v160 offset:55296
	ds_read_b128 v[226:229], v160 offset:56320
	global_load_lds_dwordx4 v[148:149], off
	s_add_i32 m0, s65, 0x2000
	s_add_u32 s66, s96, 0x40080
	v_lshl_add_u64 v[148:149], v[194:195], 0, s[82:83]
	s_addc_u32 s67, s97, 0
	s_add_i32 s65, s70, s75
	global_load_lds_dwordx4 v[148:149], off
	v_lshl_add_u64 v[148:149], s[66:67], 0, v[130:131]
	s_mov_b32 m0, s65
	s_nop 0
	global_load_lds_dwordx4 v[148:149], off
	v_lshl_add_u64 v[148:149], s[66:67], 0, v[134:135]
	s_add_i32 m0, s65, 0x2000
	s_nop 0
	global_load_lds_dwordx4 v[148:149], off
	v_lshl_add_u64 v[148:149], v[230:231], 0, s[82:83]
	s_mov_b32 m0, s55
	s_nop 0
	global_load_lds_dwordx4 v[148:149], off
	v_lshl_add_u64 v[148:149], v[232:233], 0, s[82:83]
	s_mov_b32 m0, s56
	s_nop 0
	global_load_lds_dwordx4 v[148:149], off
	s_waitcnt vmcnt(8)
	s_waitcnt lgkmcnt(0)
	s_barrier
	s_setprio 1
	s_waitcnt lgkmcnt(0)
	v_mfma_f32_16x16x32_bf16 v[60:63], v[162:165], v[198:201], v[60:63]
	v_mfma_f32_16x16x32_bf16 v[56:59], v[170:173], v[198:201], v[56:59]
	v_mfma_f32_16x16x32_bf16 v[44:47], v[162:165], v[206:209], v[44:47]
	v_mfma_f32_16x16x32_bf16 v[40:43], v[170:173], v[206:209], v[40:43]
	v_mfma_f32_16x16x32_bf16 v[28:31], v[162:165], v[214:217], v[28:31]
	v_mfma_f32_16x16x32_bf16 v[24:27], v[170:173], v[214:217], v[24:27]
	v_mfma_f32_16x16x32_bf16 v[12:15], v[162:165], v[222:225], v[12:15]
	v_mfma_f32_16x16x32_bf16 v[8:11], v[170:173], v[222:225], v[8:11]
	v_mfma_f32_16x16x32_bf16 v[60:63], v[166:169], v[202:205], v[60:63]
	v_mfma_f32_16x16x32_bf16 v[56:59], v[174:177], v[202:205], v[56:59]
	v_mfma_f32_16x16x32_bf16 v[44:47], v[166:169], v[210:213], v[44:47]
	v_mfma_f32_16x16x32_bf16 v[40:43], v[174:177], v[210:213], v[40:43]
	v_mfma_f32_16x16x32_bf16 v[28:31], v[166:169], v[218:221], v[28:31]
	v_mfma_f32_16x16x32_bf16 v[24:27], v[174:177], v[218:221], v[24:27]
	v_mfma_f32_16x16x32_bf16 v[12:15], v[166:169], v[226:229], v[12:15]
	v_mfma_f32_16x16x32_bf16 v[8:11], v[174:177], v[226:229], v[8:11]
	s_setprio 0
	s_setprio 1
	v_mfma_f32_16x16x32_bf16 v[52:55], v[178:181], v[198:201], v[52:55]
	v_mfma_f32_16x16x32_bf16 v[48:51], v[186:189], v[198:201], v[48:51]
	v_mfma_f32_16x16x32_bf16 v[36:39], v[178:181], v[206:209], v[36:39]
	v_mfma_f32_16x16x32_bf16 v[32:35], v[186:189], v[206:209], v[32:35]
	v_mfma_f32_16x16x32_bf16 v[20:23], v[178:181], v[214:217], v[20:23]
	v_mfma_f32_16x16x32_bf16 v[16:19], v[186:189], v[214:217], v[16:19]
	v_mfma_f32_16x16x32_bf16 v[4:7], v[178:181], v[222:225], v[4:7]
	v_mfma_f32_16x16x32_bf16 v[0:3], v[186:189], v[222:225], v[0:3]
	v_mfma_f32_16x16x32_bf16 v[52:55], v[182:185], v[202:205], v[52:55]
	v_mfma_f32_16x16x32_bf16 v[48:51], v[190:193], v[202:205], v[48:51]
	v_mfma_f32_16x16x32_bf16 v[36:39], v[182:185], v[210:213], v[36:39]
	v_mfma_f32_16x16x32_bf16 v[32:35], v[190:193], v[210:213], v[32:35]
	v_mfma_f32_16x16x32_bf16 v[20:23], v[182:185], v[218:221], v[20:23]
	v_mfma_f32_16x16x32_bf16 v[16:19], v[190:193], v[218:221], v[16:19]
	v_mfma_f32_16x16x32_bf16 v[4:7], v[182:185], v[226:229], v[4:7]
	v_mfma_f32_16x16x32_bf16 v[0:3], v[190:193], v[226:229], v[0:3]
	s_setprio 0
	s_barrier
	s_add_i32 s53, s53, 2
	s_add_u32 s94, s94, 0x100
	s_addc_u32 s95, s95, 0
	s_add_u32 s13, s13, 0x100
	s_addc_u32 s52, s52, 0

.LBB0_168:
	s_mov_b32 s32, 0
	s_cmp_gt_u32 s4, 63
	s_cbranch_scc1 .Lp2_code_done
	s_mov_b32 s32, 2
	s_cmp_lt_u32 s6, 4
	s_cbranch_scc1 .Lp2_code_done
	s_cmp_gt_u32 s6, 14
	s_cbranch_scc1 .Lp2_code_done
	s_mov_b32 s32, 1
	s_cmp_lt_u32 s6, 12
	s_cbranch_scc1 .Lp2_code_done
	s_mov_b32 s32, 0
